# v36 + next-iteration load condition masks also set in-block so the whole header load section is skipped (first attention unit)
# baseline (speedup 1.0000x reference)
; #define ATT_LOADK(t) do { const bf16_t* kp_ = kbase + (size_t)(64 * (t)) * 768 + kgo; _Pragma("unroll") for (int i = 0; i < 3; ++i) kreg[i] = *(const u32x4*)(kp_ + 64 * i); } while (0)
; #define ATT_LOADV(t) do { const bf16_t* vp_ = vbase + 64 * (t) + vgo; _Pragma("unroll") for (int i = 0; i < 2; ++i) vreg[i] = *(const u32x4*)(vp_ + 32 * i); } while (0)
; DI void attn_unit(LAS unsigned char* lds, const bf16_t* __restrict__ Q, const bf16_t* __restrict__ Kg, const bf16_t* __restrict__ VT, bf16_t* __restrict__ MIX, int b, int h, int c0, int nq, int desc) {
;     ...
;     if (t + 2 < nt) ATT_LOADK(TAU(t + 2));
;     if (t + 1 < nt) ATT_LOADV(taun);
;     const bool do_cur = active && tau <= cq; const bool do_next = active && (taun <= cq) && (t + 1 < nt);
.LBB0_539:
	s_add_i32 s98, s23, 131072
	s_cmp_eq_u32 s98, s99
	s_cbranch_scc1 .LBB0_543
	s_add_i32 s12, s23, 0x103
	s_cmp_lt_i32 s12, s17
	s_cselect_b64 s[26:27], -1, 0
	s_cmp_ge_i32 s12, s17
	s_cbranch_scc1 .LBB0_541
	v_mad_u64_u32 v[98:99], s[28:29], s68, v227, v[200:201]
	s_waitcnt vmcnt(0)
	global_load_dwordx4 v[178:181], v[98:99], off
	global_load_dwordx4 v[182:185], v[98:99], off offset:128
	global_load_dwordx4 v[186:189], v[98:99], off offset:256

; #define LAS __attribute__((address_space(3)))
; #define MFMA32(a, b, c) __builtin_amdgcn_mfma_f32_32x32x16_bf16((a), (b), (c), 0, 0, 0)
; DI int perm32k(int i) { return (i & 0x13) | ((i & 8) >> 1) | ((i & 4) << 1); }
; DI void attn_unit(LAS unsigned char* lds, const bf16_t* __restrict__ Q, const bf16_t* __restrict__ Kg, const bf16_t* __restrict__ VT, bf16_t* __restrict__ MIX, int b, int h, int c0, int nq, int desc) {
;     ...
;     if (t + 2 < nt) ATT_LOADK(TAU(t + 2));
;     if (t + 1 < nt) ATT_LOADV(taun);
;     const bool do_cur = active && tau <= cq; const bool do_next = active && (taun <= cq) && (t + 1 < nt);
;     if (do_cur && do_next && tau != 0) {
;       float mx = fmaxf(s0[0], s1[0]);
; #pragma unroll
;       for (int i = 1; i < 16; ++i) mx = fmaxf(mx, fmaxf(s0[i], s1[i]));
;       mx = fmaxf(mx, __shfl_xor(mx, 32));
;       const float mn = fmaxf(mrun, mx);
;       if (__builtin_amdgcn_ballot_w64(mn > mrun) != 0ull) {
;         const float alpha = __builtin_amdgcn_exp2f(mrun - mn); mrun = mn; lrun *= alpha;
; #pragma unroll
;         for (int d = 0; d < 4; ++d) O[d] = O[d] * alpha; }
; #pragma unroll
;       for (int i = 0; i < 16; ++i) { n0[i] = 0.f; n1[i] = 0.f; }
;       const LAS unsigned char* kb2 = lds + (buf ^ 1) * ATT_KB + perm32k(r31) * KROWB + 16 * hh;
;       __builtin_amdgcn_sched_barrier(0);
; #pragma unroll
;       for (int sx = 0; sx < 12; ++sx) { const bf16x8 a0 = *(const LAS bf16x8*)(kb2 + 32 * sx); const bf16x8 a1 = *(const LAS bf16x8*)(kb2 + 32 * KROWB + 32 * sx);
;         n0 = MFMA32(a0, qf[sx], n0); n1 = MFMA32(a1, qf[sx], n1);
; #pragma unroll
;         for (int j = 0; j < 3; ++j) { const int ei = 3 * sx + j; if (ei < 16) s0[ei] = __builtin_amdgcn_exp2f(s0[ei] - mrun); else if (ei < 32) s1[ei - 16] = __builtin_amdgcn_exp2f(s1[ei - 16] - mrun); }
;         __builtin_amdgcn_sched_barrier(0); }
;       float ps = 0.f;
; #pragma unroll
;       for (int i = 0; i < 16; ++i) ps += s0[i] + s1[i];
;       lrun += ps;
;       bf16x8 pf[4]; pf[0] = pack8(s0, 0); pf[1] = pack8(s0, 1); pf[2] = pack8(s1, 0); pf[3] = pack8(s1, 1);
;       const LAS unsigned char* vb = lds + 2 * ATT_KB + buf * ATT_VB + r31 * HROW + 16 * hh;
; #pragma unroll
;       for (int kk = 0; kk < 4; ++kk)
; #pragma unroll
;         for (int d = 0; d < 4; ++d) { const bf16x8 a = *(const LAS bf16x8*)(vb + d * 32 * HROW + 32 * kk); O[d] = MFMA32(a, pf[kk], O[d]); }
.Lnok_LBB0_551:
	s_waitcnt lgkmcnt(3)
	v_mfma_f32_32x32x16_bf16 v[2:17], v[234:237], v[82:85], v[2:17]
	ds_read_b128 v[234:237], v223 offset:65056
	v_add_f32_e32 v238, v238, v239
	v_add_f32_e32 v240, v240, v241
	v_mov_b64_e32 v[86:87], v[102:103]
	v_mov_b64_e32 v[94:95], v[110:111]
	s_waitcnt lgkmcnt(3)
	v_mfma_f32_32x32x16_bf16 v[50:65], v[212:215], v[90:93], v[50:65]
	ds_read_b128 v[212:215], v223 offset:51264
	v_add_f32_e32 v0, v238, v240
	v_mov_b64_e32 v[70:71], v[118:119]
	v_mov_b64_e32 v[78:79], v[126:127]
	s_waitcnt lgkmcnt(3)
	v_mfma_f32_32x32x16_bf16 v[34:49], v[218:221], v[90:93], v[34:49]
	ds_read_b128 v[218:221], v223 offset:55872
	v_add_f32_e32 v210, v210, v0
	v_mov_b64_e32 v[88:89], v[104:105]
	v_mov_b64_e32 v[96:97], v[112:113]
	s_waitcnt lgkmcnt(3)
	v_mfma_f32_32x32x16_bf16 v[18:33], v[230:233], v[90:93], v[18:33]
	ds_read_b128 v[230:233], v223 offset:60480
	s_xor_b32 s98, s12, 1
	s_mulk_i32 s98, 0x4800
	v_add_u32_e32 v229, s98, v206
	s_waitcnt vmcnt(0)
	ds_write_b128 v229, v[190:193] offset:51200
	ds_write_b128 v229, v[194:197] offset:51264
	v_max3_f32 v239, v98, v99, v100
	v_max3_f32 v241, v101, v102, v103
	s_waitcnt lgkmcnt(3)
	v_mfma_f32_32x32x16_bf16 v[2:17], v[234:237], v[90:93], v[2:17]
	ds_read_b128 v[234:237], v223 offset:65088
	v_max3_f32 v239, v239, v104, v105
	v_max3_f32 v241, v241, v106, v107
	v_mov_b64_e32 v[72:73], v[120:121]
	v_mov_b64_e32 v[80:81], v[128:129]
	s_waitcnt lgkmcnt(3)
	v_mfma_f32_32x32x16_bf16 v[50:65], v[212:215], v[66:69], v[50:65]
	ds_read_b128 v[212:215], v223 offset:51296
	v_max3_f32 v239, v239, v108, v109
	v_max3_f32 v241, v241, v110, v111
	v_mov_b64_e32 v[82:83], v[98:99]
	v_mov_b64_e32 v[84:85], v[100:101]
	s_waitcnt lgkmcnt(3)
	v_mfma_f32_32x32x16_bf16 v[34:49], v[218:221], v[66:69], v[34:49]
	ds_read_b128 v[218:221], v223 offset:55904
	v_max3_f32 v239, v239, v112, v113
	v_max3_f32 v241, v241, v114, v115
	s_add_i32 s98, s23, 0x104
	s_cmp_lt_i32 s98, s17
	s_cselect_b64 s[26:27], -1, 0
	s_cbranch_scc0 .Lnk_LBB0_551
	s_add_i32 s98, s68, 64
	v_mad_u64_u32 v[242:243], vcc, s98, v227, v[200:201]
	global_load_dwordx4 v[178:181], v[242:243], off
	global_load_dwordx4 v[182:185], v[242:243], off offset:128
	global_load_dwordx4 v[186:189], v[242:243], off offset:256
.Lnk_LBB0_551:
	v_mov_b64_e32 v[90:91], v[106:107]
	v_mov_b64_e32 v[92:93], v[108:109]
	s_waitcnt lgkmcnt(3)
	v_mfma_f32_32x32x16_bf16 v[18:33], v[230:233], v[66:69], v[18:33]
	ds_read_b128 v[230:233], v223 offset:60512
	v_max3_f32 v239, v239, v116, v117
	v_max3_f32 v241, v241, v118, v119
	s_waitcnt lgkmcnt(3)
	v_mfma_f32_32x32x16_bf16 v[2:17], v[234:237], v[66:69], v[2:17]
	ds_read_b128 v[234:237], v223 offset:65120
	v_max3_f32 v239, v239, v120, v121
	v_max3_f32 v241, v241, v122, v123
	s_add_i32 s98, s23, 0x103
	s_cmp_lt_i32 s98, s17
	s_cselect_b64 s[28:29], -1, 0
	s_cbranch_scc0 .Lnv_LBB0_551
	s_mov_b32 s100, s68
	s_mov_b32 s101, 0
	v_lshl_add_u64 v[242:243], s[100:101], 1, v[202:203]
	global_load_dwordx4 v[190:193], v[242:243], off
	global_load_dwordx4 v[194:197], v[242:243], off offset:64

; #define ATT_LOADK(t) do { const bf16_t* kp_ = kbase + (size_t)(64 * (t)) * 768 + kgo; _Pragma("unroll") for (int i = 0; i < 3; ++i) kreg[i] = *(const u32x4*)(kp_ + 64 * i); } while (0)
; #define ATT_LOADV(t) do { const bf16_t* vp_ = vbase + 64 * (t) + vgo; _Pragma("unroll") for (int i = 0; i < 2; ++i) vreg[i] = *(const u32x4*)(vp_ + 32 * i); } while (0)
; DI void attn_unit(LAS unsigned char* lds, const bf16_t* __restrict__ Q, const bf16_t* __restrict__ Kg, const bf16_t* __restrict__ VT, bf16_t* __restrict__ MIX, int b, int h, int c0, int nq, int desc) {
;     ...
;     if (t + 2 < nt) ATT_LOADK(TAU(t + 2));
;     if (t + 1 < nt) ATT_LOADV(taun);
;     const bool do_cur = active && tau <= cq; const bool do_next = active && (taun <= cq) && (t + 1 < nt);
.LBB0_2550:
	s_add_i32 s98, s23, 131072
	s_cmp_eq_u32 s98, s99
	s_cbranch_scc1 .LBB0_2554
	s_add_i32 s0, s23, 0x103
	s_cmp_lt_i32 s0, s17
	s_cselect_b64 s[26:27], -1, 0
	s_cmp_ge_i32 s0, s17
	s_cbranch_scc1 .LBB0_2552
	v_mad_u64_u32 v[98:99], s[28:29], s68, v227, v[200:201]
	s_waitcnt vmcnt(0)
	global_load_dwordx4 v[178:181], v[98:99], off
	global_load_dwordx4 v[182:185], v[98:99], off offset:128
	global_load_dwordx4 v[186:189], v[98:99], off offset:256
